# SwiGLU epilogues (P1,P8): issue the 8 rowsq loads together and wait once instead of load+vmcnt(0) per 16-row group; on top of k4
# speedup vs baseline: 1.0234x; 1.0006x over previous
; __device__ __forceinline__ unsigned cvt_pk_bf16(float lo, float hi) { unsigned r; asm volatile("v_cvt_pk_bf16_f32 %0, %1, %2" : "=v"(r) : "v"(lo), "v"(hi)); return r; }
;     __device__ __forceinline__ void operator()(const pg8::f32x4 (&acc)[2][2][4][2], const pg8::Unit& u, int wr, int wc, int fr, int fq) const {
;         const int row0 = u.pm * 256 + wr * 64 + fr, col0 = u.pn * 128 + wc * 32 + 8 * fq;
; #pragma unroll
;         for (int ai = 0; ai < 2; ++ai)
; #pragma unroll
;             for (int m = 0; m < 4; ++m) {
;                 const int row = row0 + ai * 128 + m * 16;
;                 const float rs = rsqrtf(rowsq[row] * (1.f / 1024.f) + 1e-6f);
;                 float h[8];
; #pragma unroll
;                 for (int n = 0; n < 2; ++n)
; #pragma unroll
;                     for (int j = 0; j < 4; ++j) { const float g = acc[ai][0][m][n][j] * rs, up = acc[ai][1][m][n][j] * rs; h[4 * n + j] = g * __builtin_amdgcn_rcpf(1.f + __expf(-g)) * up; }
;                 u32x4 w; w.x = cvt_pk_bf16(h[0], h[1]); w.y = cvt_pk_bf16(h[2], h[3]); w.z = cvt_pk_bf16(h[4], h[5]); w.w = cvt_pk_bf16(h[6], h[7]);
;                 *(u32x4*)(H + (size_t)row * DFF + col0) = w;
.LBB0_115:
	v_lshl_add_u32 v142, s3, 8, v146
	v_ashrrev_i32_e32 v143, 31, v142
	v_lshl_add_u64 v[144:145], v[142:143], 2, s[18:19]
	global_load_dword v143, v[144:145], off
	global_load_dword v230, v[144:145], off offset:64
	global_load_dword v231, v[144:145], off offset:128
	global_load_dword v232, v[144:145], off offset:192
	global_load_dword v233, v[144:145], off offset:512
	global_load_dword v234, v[144:145], off offset:576
	global_load_dword v235, v[144:145], off offset:640
	global_load_dword v236, v[144:145], off offset:704
	v_mov_b32_e32 v162, v118
	v_mov_b32_e32 v163, v114
	v_mov_b32_e32 v114, v119
	v_lshl_or_b32 v158, s56, 7, v152
	v_mov_b32_e32 v160, v124
	v_mov_b32_e32 v161, v120
	v_mov_b32_e32 v120, v125
	v_mov_b32_e32 v124, v126
	v_mov_b32_e32 v125, v122
	v_mov_b32_e32 v122, v127
	v_mov_b32_e32 v126, v116
	v_mov_b32_e32 v127, v112
	v_mov_b32_e32 v112, v117
	v_mov_b64_e32 v[116:117], s[22:23]
	v_ashrrev_i32_e32 v159, 31, v158
	v_mad_i64_i32 v[166:167], s[56:57], v142, s69, v[116:117]
	s_cmp_lg_u32 s3, 64
	s_waitcnt vmcnt(0)
	v_fmamk_f32 v118, v143, 0x3a800000, v156
	v_mul_f32_e32 v119, 0x4b800000, v118
	v_cmp_gt_f32_e32 vcc, s68, v118
	s_nop 1
	v_cndmask_b32_e32 v118, v118, v119, vcc
	v_rsq_f32_e32 v143, v118
	v_lshlrev_b64 v[118:119], 1, v[158:159]
	v_lshl_add_u64 v[158:159], v[166:167], 0, v[118:119]
	v_mul_f32_e32 v157, 0x45800000, v143
	v_cndmask_b32_e32 v166, v143, v157, vcc
	v_pk_mul_f32 v[114:115], v[114:115], v[166:167] op_sel_hi:[1,0]
	v_pk_mul_f32 v[160:161], v[160:161], v[166:167] op_sel_hi:[1,0]
	v_pk_mul_f32 v[120:121], v[120:121], v[166:167] op_sel_hi:[1,0]
	v_pk_mul_f32 v[124:125], v[124:125], v[166:167] op_sel_hi:[1,0]
	v_pk_mul_f32 v[122:123], v[122:123], v[166:167] op_sel_hi:[1,0]
	v_pk_mul_f32 v[126:127], v[126:127], v[166:167] op_sel_hi:[1,0]
	v_pk_mul_f32 v[112:113], v[112:113], v[166:167] op_sel_hi:[1,0]
	v_pk_mul_f32 v[162:163], v[162:163], v[166:167] op_sel_hi:[1,0]
	v_mul_f32_e32 v171, 0xbfb8aa3b, v115
	v_mul_f32_e32 v143, 0xbfb8aa3b, v161
	v_mul_f32_e32 v157, 0xbfb8aa3b, v121
	v_mul_f32_e32 v166, 0xbfb8aa3b, v125
	v_mul_f32_e32 v167, 0xbfb8aa3b, v123
	v_mul_f32_e32 v168, 0xbfb8aa3b, v127
	v_mul_f32_e32 v169, 0xbfb8aa3b, v113
	v_mul_f32_e32 v170, 0xbfb8aa3b, v163
	v_exp_f32_e32 v171, v171
	v_exp_f32_e32 v143, v143
	v_exp_f32_e32 v157, v157
	v_exp_f32_e32 v166, v166
	v_exp_f32_e32 v167, v167
	v_exp_f32_e32 v168, v168
	v_exp_f32_e32 v169, v169
	v_exp_f32_e32 v170, v170
	v_add_f32_e32 v171, 1.0, v171
	v_add_f32_e32 v143, 1.0, v143
	v_add_f32_e32 v157, 1.0, v157
	v_add_f32_e32 v166, 1.0, v166
	v_add_f32_e32 v167, 1.0, v167
	v_add_f32_e32 v168, 1.0, v168
	v_add_f32_e32 v169, 1.0, v169
	v_add_f32_e32 v170, 1.0, v170
	v_rcp_f32_e32 v171, v171
	v_rcp_f32_e32 v143, v143
	v_rcp_f32_e32 v157, v157
	v_rcp_f32_e32 v166, v166
	v_rcp_f32_e32 v167, v167
	v_rcp_f32_e32 v168, v168
	v_rcp_f32_e32 v169, v169
	v_rcp_f32_e32 v170, v170
	v_mul_f32_e32 v115, v115, v171
	v_mul_f32_e32 v143, v161, v143
	v_mul_f32_e32 v121, v121, v157
	v_mul_f32_e32 v125, v125, v166
	v_mul_f32_e32 v123, v123, v167
	v_mul_f32_e32 v127, v127, v168
	v_mul_f32_e32 v113, v113, v169
	v_mul_f32_e32 v157, v163, v170
	v_mul_f32_e32 v115, v114, v115
	v_mul_f32_e32 v143, v160, v143
	v_mul_f32_e32 v120, v120, v121
	v_mul_f32_e32 v121, v124, v125
	v_mul_f32_e32 v122, v122, v123
	v_mul_f32_e32 v123, v126, v127
	v_mul_f32_e32 v124, v112, v113
	v_mul_f32_e32 v125, v162, v157
	v_cvt_pk_bf16_f32 v112, v143, v120
	v_cvt_pk_bf16_f32 v113, v121, v122
	v_cvt_pk_bf16_f32 v114, v123, v124
	v_cvt_pk_bf16_f32 v115, v125, v115
	global_store_dwordx4 v[158:159], v[112:115], off
	s_nop 1
	v_mov_b32_e32 v114, v230
	s_nop 0
	v_mov_b32_e32 v113, v104
	v_mov_b32_e32 v104, v109
	v_mov_b32_e32 v109, v106
	v_mov_b32_e32 v106, v111
	v_mov_b32_e32 v111, v96
	v_mov_b32_e32 v96, v101
	v_mov_b32_e32 v101, v98
	v_mov_b32_e32 v98, v103
	v_mov_b32_e32 v112, v108
	v_mov_b32_e32 v108, v110
	v_mov_b32_e32 v110, v100
	v_mov_b32_e32 v100, v102
	v_or_b32_e32 v102, 16, v142
	s_nop 0
	v_fmamk_f32 v103, v114, 0x3a800000, v156
	v_mul_f32_e32 v114, 0x4b800000, v103
	v_cmp_gt_f32_e32 vcc, s68, v103
	s_nop 1
	v_cndmask_b32_e32 v103, v103, v114, vcc
	v_rsq_f32_e32 v114, v103
	v_mad_i64_i32 v[102:103], s[56:57], v102, s69, v[116:117]
	v_lshl_add_u64 v[102:103], v[102:103], 0, v[118:119]
	v_mul_f32_e32 v115, 0x45800000, v114
	v_cndmask_b32_e32 v114, v114, v115, vcc
	v_pk_mul_f32 v[98:99], v[98:99], v[114:115] op_sel_hi:[1,0]
	v_pk_mul_f32 v[112:113], v[112:113], v[114:115] op_sel_hi:[1,0]
	v_pk_mul_f32 v[104:105], v[104:105], v[114:115] op_sel_hi:[1,0]
	v_pk_mul_f32 v[108:109], v[108:109], v[114:115] op_sel_hi:[1,0]
	v_pk_mul_f32 v[106:107], v[106:107], v[114:115] op_sel_hi:[1,0]
	v_pk_mul_f32 v[110:111], v[110:111], v[114:115] op_sel_hi:[1,0]
	v_pk_mul_f32 v[96:97], v[96:97], v[114:115] op_sel_hi:[1,0]
	v_pk_mul_f32 v[100:101], v[100:101], v[114:115] op_sel_hi:[1,0]
	v_mul_f32_e32 v125, 0xbfb8aa3b, v99
	v_mul_f32_e32 v114, 0xbfb8aa3b, v113
	v_mul_f32_e32 v115, 0xbfb8aa3b, v105
	v_mul_f32_e32 v120, 0xbfb8aa3b, v109
	v_mul_f32_e32 v121, 0xbfb8aa3b, v107
	v_mul_f32_e32 v122, 0xbfb8aa3b, v111
	v_mul_f32_e32 v123, 0xbfb8aa3b, v97
	v_mul_f32_e32 v124, 0xbfb8aa3b, v101
	v_exp_f32_e32 v125, v125
	v_exp_f32_e32 v114, v114
	v_exp_f32_e32 v115, v115
	v_exp_f32_e32 v120, v120
	v_exp_f32_e32 v121, v121
	v_exp_f32_e32 v122, v122
	v_exp_f32_e32 v123, v123
	v_exp_f32_e32 v124, v124
	v_add_f32_e32 v125, 1.0, v125
	v_add_f32_e32 v114, 1.0, v114
	v_add_f32_e32 v115, 1.0, v115
	v_add_f32_e32 v120, 1.0, v120
	v_add_f32_e32 v121, 1.0, v121
	v_add_f32_e32 v122, 1.0, v122
	v_add_f32_e32 v123, 1.0, v123
	v_add_f32_e32 v124, 1.0, v124
; __device__ __forceinline__ unsigned cvt_pk_bf16(float lo, float hi) { unsigned r; asm volatile("v_cvt_pk_bf16_f32 %0, %1, %2" : "=v"(r) : "v"(lo), "v"(hi)); return r; }
;     __device__ __forceinline__ void operator()(const pg8::f32x4 (&acc)[2][2][4][2], const pg8::Unit& u, int wr, int wc, int fr, int fq) const {
;         const int row0 = u.pm * 256 + wr * 64 + fr, col0 = u.pn * 128 + wc * 32 + 8 * fq;
; #pragma unroll
;         for (int ai = 0; ai < 2; ++ai)
; #pragma unroll
;             for (int m = 0; m < 4; ++m) {
;                 const int row = row0 + ai * 128 + m * 16;
;                 const float rs = rsqrtf(rowsq[row] * (1.f / 1024.f) + 1e-6f);
;                 float h[8];
; #pragma unroll
;                 for (int n = 0; n < 2; ++n)
; #pragma unroll
;                     for (int j = 0; j < 4; ++j) { const float g = acc[ai][0][m][n][j] * rs, up = acc[ai][1][m][n][j] * rs; h[4 * n + j] = g * __builtin_amdgcn_rcpf(1.f + __expf(-g)) * up; }
;                 u32x4 w; w.x = cvt_pk_bf16(h[0], h[1]); w.y = cvt_pk_bf16(h[2], h[3]); w.z = cvt_pk_bf16(h[4], h[5]); w.w = cvt_pk_bf16(h[6], h[7]);
;                 *(u32x4*)(H + (size_t)row * DFF + col0) = w;
	v_rcp_f32_e32 v125, v125
	v_rcp_f32_e32 v114, v114
	v_rcp_f32_e32 v115, v115
	v_rcp_f32_e32 v120, v120
	v_rcp_f32_e32 v121, v121
	v_rcp_f32_e32 v122, v122
	v_rcp_f32_e32 v123, v123
	v_rcp_f32_e32 v124, v124
	v_mul_f32_e32 v99, v99, v125
	v_mul_f32_e32 v113, v113, v114
	v_mul_f32_e32 v105, v105, v115
	v_mul_f32_e32 v109, v109, v120
	v_mul_f32_e32 v107, v107, v121
	v_mul_f32_e32 v111, v111, v122
	v_mul_f32_e32 v97, v97, v123
	v_mul_f32_e32 v101, v101, v124
	v_mul_f32_e32 v99, v98, v99
	v_mul_f32_e32 v112, v112, v113
	v_mul_f32_e32 v104, v104, v105
	v_mul_f32_e32 v105, v108, v109
	v_mul_f32_e32 v106, v106, v107
	v_mul_f32_e32 v107, v110, v111
	v_mul_f32_e32 v108, v96, v97
	v_mul_f32_e32 v100, v100, v101
	v_cvt_pk_bf16_f32 v96, v112, v104
	v_cvt_pk_bf16_f32 v97, v105, v106
	v_cvt_pk_bf16_f32 v98, v107, v108
	v_cvt_pk_bf16_f32 v99, v100, v99
	global_store_dwordx4 v[102:103], v[96:99], off
	s_nop 1
	v_mov_b32_e32 v98, v231
	s_nop 0
	v_mov_b32_e32 v97, v88
	v_mov_b32_e32 v88, v93
	v_mov_b32_e32 v93, v90
	v_mov_b32_e32 v90, v95
	v_mov_b32_e32 v95, v80
	v_mov_b32_e32 v80, v85
	v_mov_b32_e32 v85, v82
	v_mov_b32_e32 v82, v87
	v_mov_b32_e32 v96, v92
	v_mov_b32_e32 v92, v94
	v_mov_b32_e32 v94, v84
	v_mov_b32_e32 v84, v86
	v_or_b32_e32 v86, 32, v142
	s_nop 0
	v_fmamk_f32 v87, v98, 0x3a800000, v156
	v_mul_f32_e32 v98, 0x4b800000, v87
	v_cmp_gt_f32_e32 vcc, s68, v87
	s_nop 1
	v_cndmask_b32_e32 v87, v87, v98, vcc
	v_rsq_f32_e32 v98, v87
	v_mad_i64_i32 v[86:87], s[56:57], v86, s69, v[116:117]
	v_lshl_add_u64 v[86:87], v[86:87], 0, v[118:119]
	v_mul_f32_e32 v99, 0x45800000, v98
	v_cndmask_b32_e32 v98, v98, v99, vcc
	v_pk_mul_f32 v[82:83], v[82:83], v[98:99] op_sel_hi:[1,0]
	v_pk_mul_f32 v[96:97], v[96:97], v[98:99] op_sel_hi:[1,0]
	v_pk_mul_f32 v[88:89], v[88:89], v[98:99] op_sel_hi:[1,0]
	v_pk_mul_f32 v[92:93], v[92:93], v[98:99] op_sel_hi:[1,0]
	v_pk_mul_f32 v[90:91], v[90:91], v[98:99] op_sel_hi:[1,0]
	v_pk_mul_f32 v[94:95], v[94:95], v[98:99] op_sel_hi:[1,0]
	v_pk_mul_f32 v[80:81], v[80:81], v[98:99] op_sel_hi:[1,0]
	v_pk_mul_f32 v[84:85], v[84:85], v[98:99] op_sel_hi:[1,0]
	v_mul_f32_e32 v105, 0xbfb8aa3b, v83
	v_mul_f32_e32 v98, 0xbfb8aa3b, v97
	v_mul_f32_e32 v99, 0xbfb8aa3b, v89
	v_mul_f32_e32 v100, 0xbfb8aa3b, v93
	v_mul_f32_e32 v101, 0xbfb8aa3b, v91
	v_mul_f32_e32 v102, 0xbfb8aa3b, v95
	v_mul_f32_e32 v103, 0xbfb8aa3b, v81
	v_mul_f32_e32 v104, 0xbfb8aa3b, v85
	v_exp_f32_e32 v105, v105
	v_exp_f32_e32 v98, v98
	v_exp_f32_e32 v99, v99
	v_exp_f32_e32 v100, v100
	v_exp_f32_e32 v101, v101
	v_exp_f32_e32 v102, v102
	v_exp_f32_e32 v103, v103
	v_exp_f32_e32 v104, v104
	v_add_f32_e32 v105, 1.0, v105
	v_add_f32_e32 v98, 1.0, v98
	v_add_f32_e32 v99, 1.0, v99
	v_add_f32_e32 v100, 1.0, v100
	v_add_f32_e32 v101, 1.0, v101
	v_add_f32_e32 v102, 1.0, v102
	v_add_f32_e32 v103, 1.0, v103
	v_add_f32_e32 v104, 1.0, v104
	v_rcp_f32_e32 v105, v105
	v_rcp_f32_e32 v98, v98
	v_rcp_f32_e32 v99, v99
	v_rcp_f32_e32 v100, v100
	v_rcp_f32_e32 v101, v101
	v_rcp_f32_e32 v102, v102
	v_rcp_f32_e32 v103, v103
	v_rcp_f32_e32 v104, v104
	v_mul_f32_e32 v83, v83, v105
	v_mul_f32_e32 v97, v97, v98
	v_mul_f32_e32 v89, v89, v99
	v_mul_f32_e32 v93, v93, v100
	v_mul_f32_e32 v91, v91, v101
	v_mul_f32_e32 v95, v95, v102
	v_mul_f32_e32 v81, v81, v103
	v_mul_f32_e32 v85, v85, v104
	v_mul_f32_e32 v83, v82, v83
	v_mul_f32_e32 v96, v96, v97
	v_mul_f32_e32 v88, v88, v89
	v_mul_f32_e32 v89, v92, v93
	v_mul_f32_e32 v90, v90, v91
	v_mul_f32_e32 v91, v94, v95
	v_mul_f32_e32 v92, v80, v81
	v_mul_f32_e32 v84, v84, v85
	v_cvt_pk_bf16_f32 v80, v96, v88
	v_cvt_pk_bf16_f32 v81, v89, v90
	v_cvt_pk_bf16_f32 v82, v91, v92
	v_cvt_pk_bf16_f32 v83, v84, v83
	global_store_dwordx4 v[86:87], v[80:83], off
	s_nop 1
	v_mov_b32_e32 v82, v232
	s_nop 0
	v_mov_b32_e32 v81, v72
	v_mov_b32_e32 v72, v77
	v_mov_b32_e32 v77, v74
	v_mov_b32_e32 v74, v79
	v_mov_b32_e32 v79, v64
	v_mov_b32_e32 v64, v69
	v_mov_b32_e32 v69, v66
	v_mov_b32_e32 v66, v71
	v_mov_b32_e32 v80, v76
	v_mov_b32_e32 v76, v78
	v_mov_b32_e32 v78, v68
	v_mov_b32_e32 v68, v70
	v_or_b32_e32 v70, 48, v142
	s_nop 0
	v_fmamk_f32 v71, v82, 0x3a800000, v156
	v_mul_f32_e32 v82, 0x4b800000, v71
	v_cmp_gt_f32_e32 vcc, s68, v71
	s_nop 1
	v_cndmask_b32_e32 v71, v71, v82, vcc
	v_rsq_f32_e32 v82, v71
	v_mad_i64_i32 v[70:71], s[56:57], v70, s69, v[116:117]
	v_lshl_add_u64 v[70:71], v[70:71], 0, v[118:119]
	v_mul_f32_e32 v83, 0x45800000, v82
	v_cndmask_b32_e32 v82, v82, v83, vcc
	v_pk_mul_f32 v[66:67], v[66:67], v[82:83] op_sel_hi:[1,0]
	v_pk_mul_f32 v[80:81], v[80:81], v[82:83] op_sel_hi:[1,0]
	v_pk_mul_f32 v[72:73], v[72:73], v[82:83] op_sel_hi:[1,0]
	v_pk_mul_f32 v[76:77], v[76:77], v[82:83] op_sel_hi:[1,0]
	v_pk_mul_f32 v[74:75], v[74:75], v[82:83] op_sel_hi:[1,0]
	v_pk_mul_f32 v[78:79], v[78:79], v[82:83] op_sel_hi:[1,0]
	v_pk_mul_f32 v[64:65], v[64:65], v[82:83] op_sel_hi:[1,0]
	v_pk_mul_f32 v[68:69], v[68:69], v[82:83] op_sel_hi:[1,0]
	v_mul_f32_e32 v89, 0xbfb8aa3b, v67
	v_mul_f32_e32 v82, 0xbfb8aa3b, v81
	v_mul_f32_e32 v83, 0xbfb8aa3b, v73
	v_mul_f32_e32 v84, 0xbfb8aa3b, v77
	v_mul_f32_e32 v85, 0xbfb8aa3b, v75
	v_mul_f32_e32 v86, 0xbfb8aa3b, v79
	v_mul_f32_e32 v87, 0xbfb8aa3b, v65
	v_mul_f32_e32 v88, 0xbfb8aa3b, v69
	v_exp_f32_e32 v89, v89
	v_exp_f32_e32 v82, v82
	v_exp_f32_e32 v83, v83
	v_exp_f32_e32 v84, v84
	v_exp_f32_e32 v85, v85
	v_exp_f32_e32 v86, v86
	v_exp_f32_e32 v87, v87
	v_exp_f32_e32 v88, v88
	v_add_f32_e32 v89, 1.0, v89
	v_add_f32_e32 v82, 1.0, v82
	v_add_f32_e32 v83, 1.0, v83
	v_add_f32_e32 v84, 1.0, v84
	v_add_f32_e32 v85, 1.0, v85
	v_add_f32_e32 v86, 1.0, v86
	v_add_f32_e32 v87, 1.0, v87
	v_add_f32_e32 v88, 1.0, v88
	v_rcp_f32_e32 v89, v89
	v_rcp_f32_e32 v82, v82
; __device__ __forceinline__ unsigned cvt_pk_bf16(float lo, float hi) { unsigned r; asm volatile("v_cvt_pk_bf16_f32 %0, %1, %2" : "=v"(r) : "v"(lo), "v"(hi)); return r; }
;     __device__ __forceinline__ void operator()(const pg8::f32x4 (&acc)[2][2][4][2], const pg8::Unit& u, int wr, int wc, int fr, int fq) const {
;         const int row0 = u.pm * 256 + wr * 64 + fr, col0 = u.pn * 128 + wc * 32 + 8 * fq;
; #pragma unroll
;         for (int ai = 0; ai < 2; ++ai)
; #pragma unroll
;             for (int m = 0; m < 4; ++m) {
;                 const int row = row0 + ai * 128 + m * 16;
;                 const float rs = rsqrtf(rowsq[row] * (1.f / 1024.f) + 1e-6f);
;                 float h[8];
; #pragma unroll
;                 for (int n = 0; n < 2; ++n)
; #pragma unroll
;                     for (int j = 0; j < 4; ++j) { const float g = acc[ai][0][m][n][j] * rs, up = acc[ai][1][m][n][j] * rs; h[4 * n + j] = g * __builtin_amdgcn_rcpf(1.f + __expf(-g)) * up; }
;                 u32x4 w; w.x = cvt_pk_bf16(h[0], h[1]); w.y = cvt_pk_bf16(h[2], h[3]); w.z = cvt_pk_bf16(h[4], h[5]); w.w = cvt_pk_bf16(h[6], h[7]);
;                 *(u32x4*)(H + (size_t)row * DFF + col0) = w;
	v_rcp_f32_e32 v83, v83
	v_rcp_f32_e32 v84, v84
	v_rcp_f32_e32 v85, v85
	v_rcp_f32_e32 v86, v86
	v_rcp_f32_e32 v87, v87
	v_rcp_f32_e32 v88, v88
	v_mul_f32_e32 v67, v67, v89
	v_mul_f32_e32 v81, v81, v82
	v_mul_f32_e32 v73, v73, v83
	v_mul_f32_e32 v77, v77, v84
	v_mul_f32_e32 v75, v75, v85
	v_mul_f32_e32 v79, v79, v86
	v_mul_f32_e32 v65, v65, v87
	v_mul_f32_e32 v69, v69, v88
	v_mul_f32_e32 v67, v66, v67
	v_mul_f32_e32 v80, v80, v81
	v_mul_f32_e32 v72, v72, v73
	v_mul_f32_e32 v73, v76, v77
	v_mul_f32_e32 v74, v74, v75
	v_mul_f32_e32 v75, v78, v79
	v_mul_f32_e32 v76, v64, v65
	v_mul_f32_e32 v68, v68, v69
	v_cvt_pk_bf16_f32 v64, v80, v72
	v_cvt_pk_bf16_f32 v65, v73, v74
	v_cvt_pk_bf16_f32 v66, v75, v76
	v_cvt_pk_bf16_f32 v67, v68, v67
	global_store_dwordx4 v[70:71], v[64:67], off
	s_nop 1
	v_mov_b32_e32 v66, v233
	s_nop 0
	v_mov_b32_e32 v65, v56
	v_mov_b32_e32 v56, v61
	v_mov_b32_e32 v61, v58
	v_mov_b32_e32 v58, v63
	v_mov_b32_e32 v63, v48
	v_mov_b32_e32 v48, v53
	v_mov_b32_e32 v53, v50
	v_mov_b32_e32 v50, v55
	v_mov_b32_e32 v64, v60
	v_mov_b32_e32 v60, v62
	v_mov_b32_e32 v62, v52
	v_mov_b32_e32 v52, v54
	v_add_u32_e32 v54, 0x80, v142
	s_nop 0
	v_fmamk_f32 v55, v66, 0x3a800000, v156
	v_mul_f32_e32 v66, 0x4b800000, v55
	v_cmp_gt_f32_e32 vcc, s68, v55
	s_nop 1
	v_cndmask_b32_e32 v55, v55, v66, vcc
	v_rsq_f32_e32 v66, v55
	v_mad_i64_i32 v[54:55], s[56:57], v54, s69, v[116:117]
	v_lshl_add_u64 v[54:55], v[54:55], 0, v[118:119]
	v_mul_f32_e32 v67, 0x45800000, v66
	v_cndmask_b32_e32 v66, v66, v67, vcc
	v_pk_mul_f32 v[50:51], v[50:51], v[66:67] op_sel_hi:[1,0]
	v_pk_mul_f32 v[64:65], v[64:65], v[66:67] op_sel_hi:[1,0]
	v_pk_mul_f32 v[56:57], v[56:57], v[66:67] op_sel_hi:[1,0]
	v_pk_mul_f32 v[60:61], v[60:61], v[66:67] op_sel_hi:[1,0]
	v_pk_mul_f32 v[58:59], v[58:59], v[66:67] op_sel_hi:[1,0]
	v_pk_mul_f32 v[62:63], v[62:63], v[66:67] op_sel_hi:[1,0]
	v_pk_mul_f32 v[48:49], v[48:49], v[66:67] op_sel_hi:[1,0]
	v_pk_mul_f32 v[52:53], v[52:53], v[66:67] op_sel_hi:[1,0]
	v_mul_f32_e32 v73, 0xbfb8aa3b, v51
	v_mul_f32_e32 v66, 0xbfb8aa3b, v65
	v_mul_f32_e32 v67, 0xbfb8aa3b, v57
	v_mul_f32_e32 v68, 0xbfb8aa3b, v61
	v_mul_f32_e32 v69, 0xbfb8aa3b, v59
	v_mul_f32_e32 v70, 0xbfb8aa3b, v63
	v_mul_f32_e32 v71, 0xbfb8aa3b, v49
	v_mul_f32_e32 v72, 0xbfb8aa3b, v53
	v_exp_f32_e32 v73, v73
	v_exp_f32_e32 v66, v66
	v_exp_f32_e32 v67, v67
	v_exp_f32_e32 v68, v68
	v_exp_f32_e32 v69, v69
	v_exp_f32_e32 v70, v70
	v_exp_f32_e32 v71, v71
	v_exp_f32_e32 v72, v72
	v_add_f32_e32 v73, 1.0, v73
	v_add_f32_e32 v66, 1.0, v66
	v_add_f32_e32 v67, 1.0, v67
	v_add_f32_e32 v68, 1.0, v68
	v_add_f32_e32 v69, 1.0, v69
	v_add_f32_e32 v70, 1.0, v70
	v_add_f32_e32 v71, 1.0, v71
	v_add_f32_e32 v72, 1.0, v72
	v_rcp_f32_e32 v73, v73
	v_rcp_f32_e32 v66, v66
	v_rcp_f32_e32 v67, v67
	v_rcp_f32_e32 v68, v68
	v_rcp_f32_e32 v69, v69
	v_rcp_f32_e32 v70, v70
	v_rcp_f32_e32 v71, v71
	v_rcp_f32_e32 v72, v72
	v_mul_f32_e32 v51, v51, v73
	v_mul_f32_e32 v65, v65, v66
	v_mul_f32_e32 v57, v57, v67
	v_mul_f32_e32 v61, v61, v68
	v_mul_f32_e32 v59, v59, v69
	v_mul_f32_e32 v63, v63, v70
	v_mul_f32_e32 v49, v49, v71
	v_mul_f32_e32 v53, v53, v72
	v_mul_f32_e32 v51, v50, v51
	v_mul_f32_e32 v64, v64, v65
	v_mul_f32_e32 v56, v56, v57
	v_mul_f32_e32 v57, v60, v61
	v_mul_f32_e32 v58, v58, v59
	v_mul_f32_e32 v59, v62, v63
	v_mul_f32_e32 v60, v48, v49
	v_mul_f32_e32 v52, v52, v53
	v_cvt_pk_bf16_f32 v48, v64, v56
	v_cvt_pk_bf16_f32 v49, v57, v58
	v_cvt_pk_bf16_f32 v50, v59, v60
	v_cvt_pk_bf16_f32 v51, v52, v51
	global_store_dwordx4 v[54:55], v[48:51], off
	s_nop 1
	v_mov_b32_e32 v50, v234
	s_nop 0
	v_mov_b32_e32 v49, v40
	v_mov_b32_e32 v40, v45
	v_mov_b32_e32 v45, v42
	v_mov_b32_e32 v42, v47
	v_mov_b32_e32 v47, v32
	v_mov_b32_e32 v32, v37
	v_mov_b32_e32 v37, v34
	v_mov_b32_e32 v34, v39
	v_mov_b32_e32 v48, v44
	v_mov_b32_e32 v44, v46
	v_mov_b32_e32 v46, v36
	v_mov_b32_e32 v36, v38
	v_add_u32_e32 v38, 0x90, v142
	s_nop 0
	v_fmamk_f32 v39, v50, 0x3a800000, v156
	v_mul_f32_e32 v50, 0x4b800000, v39
	v_cmp_gt_f32_e32 vcc, s68, v39
	s_nop 1
	v_cndmask_b32_e32 v39, v39, v50, vcc
	v_rsq_f32_e32 v50, v39
	v_mad_i64_i32 v[38:39], s[56:57], v38, s69, v[116:117]
	v_lshl_add_u64 v[38:39], v[38:39], 0, v[118:119]
	v_mul_f32_e32 v51, 0x45800000, v50
	v_cndmask_b32_e32 v50, v50, v51, vcc
	v_pk_mul_f32 v[34:35], v[34:35], v[50:51] op_sel_hi:[1,0]
	v_pk_mul_f32 v[48:49], v[48:49], v[50:51] op_sel_hi:[1,0]
	v_pk_mul_f32 v[40:41], v[40:41], v[50:51] op_sel_hi:[1,0]
	v_pk_mul_f32 v[44:45], v[44:45], v[50:51] op_sel_hi:[1,0]
	v_pk_mul_f32 v[42:43], v[42:43], v[50:51] op_sel_hi:[1,0]
	v_pk_mul_f32 v[46:47], v[46:47], v[50:51] op_sel_hi:[1,0]
	v_pk_mul_f32 v[32:33], v[32:33], v[50:51] op_sel_hi:[1,0]
	v_pk_mul_f32 v[36:37], v[36:37], v[50:51] op_sel_hi:[1,0]
	v_mul_f32_e32 v57, 0xbfb8aa3b, v35
	v_mul_f32_e32 v50, 0xbfb8aa3b, v49
	v_mul_f32_e32 v51, 0xbfb8aa3b, v41
	v_mul_f32_e32 v52, 0xbfb8aa3b, v45
	v_mul_f32_e32 v53, 0xbfb8aa3b, v43
	v_mul_f32_e32 v54, 0xbfb8aa3b, v47
	v_mul_f32_e32 v55, 0xbfb8aa3b, v33
	v_mul_f32_e32 v56, 0xbfb8aa3b, v37
	v_exp_f32_e32 v57, v57
	v_exp_f32_e32 v50, v50
	v_exp_f32_e32 v51, v51
	v_exp_f32_e32 v52, v52
	v_exp_f32_e32 v53, v53
	v_exp_f32_e32 v54, v54
	v_exp_f32_e32 v55, v55
	v_exp_f32_e32 v56, v56
	v_add_f32_e32 v57, 1.0, v57
	v_add_f32_e32 v50, 1.0, v50
	v_add_f32_e32 v51, 1.0, v51
	v_add_f32_e32 v52, 1.0, v52
	v_add_f32_e32 v53, 1.0, v53
	v_add_f32_e32 v54, 1.0, v54
	v_add_f32_e32 v55, 1.0, v55
	v_add_f32_e32 v56, 1.0, v56
	v_rcp_f32_e32 v57, v57
	v_rcp_f32_e32 v50, v50
	v_rcp_f32_e32 v51, v51
	v_rcp_f32_e32 v52, v52
	v_rcp_f32_e32 v53, v53
	v_rcp_f32_e32 v54, v54
	v_rcp_f32_e32 v55, v55
	v_rcp_f32_e32 v56, v56
; __device__ __forceinline__ unsigned cvt_pk_bf16(float lo, float hi) { unsigned r; asm volatile("v_cvt_pk_bf16_f32 %0, %1, %2" : "=v"(r) : "v"(lo), "v"(hi)); return r; }
;     __device__ __forceinline__ void operator()(const pg8::f32x4 (&acc)[2][2][4][2], const pg8::Unit& u, int wr, int wc, int fr, int fq) const {
;         const int row0 = u.pm * 256 + wr * 64 + fr, col0 = u.pn * 128 + wc * 32 + 8 * fq;
; #pragma unroll
;         for (int ai = 0; ai < 2; ++ai)
; #pragma unroll
;             for (int m = 0; m < 4; ++m) {
;                 const int row = row0 + ai * 128 + m * 16;
;                 const float rs = rsqrtf(rowsq[row] * (1.f / 1024.f) + 1e-6f);
;                 float h[8];
; #pragma unroll
;                 for (int n = 0; n < 2; ++n)
; #pragma unroll
;                     for (int j = 0; j < 4; ++j) { const float g = acc[ai][0][m][n][j] * rs, up = acc[ai][1][m][n][j] * rs; h[4 * n + j] = g * __builtin_amdgcn_rcpf(1.f + __expf(-g)) * up; }
;                 u32x4 w; w.x = cvt_pk_bf16(h[0], h[1]); w.y = cvt_pk_bf16(h[2], h[3]); w.z = cvt_pk_bf16(h[4], h[5]); w.w = cvt_pk_bf16(h[6], h[7]);
;                 *(u32x4*)(H + (size_t)row * DFF + col0) = w;
;     __device__ __forceinline__ void done(const pg8::Unit& u) const {
;         if (u.pm == nM) { __builtin_amdgcn_fence(__ATOMIC_RELEASE, "agent"); if ((threadIdx.x & 63) == 0) __hip_atomic_fetch_add(cnt, 1u, __ATOMIC_RELAXED, __HIP_MEMORY_SCOPE_AGENT); }
;     }
	v_mul_f32_e32 v35, v35, v57
	v_mul_f32_e32 v49, v49, v50
	v_mul_f32_e32 v41, v41, v51
	v_mul_f32_e32 v45, v45, v52
	v_mul_f32_e32 v43, v43, v53
	v_mul_f32_e32 v47, v47, v54
	v_mul_f32_e32 v33, v33, v55
	v_mul_f32_e32 v37, v37, v56
	v_mul_f32_e32 v35, v34, v35
	v_mul_f32_e32 v48, v48, v49
	v_mul_f32_e32 v40, v40, v41
	v_mul_f32_e32 v41, v44, v45
	v_mul_f32_e32 v42, v42, v43
	v_mul_f32_e32 v43, v46, v47
	v_mul_f32_e32 v44, v32, v33
	v_mul_f32_e32 v36, v36, v37
	v_cvt_pk_bf16_f32 v32, v48, v40
	v_cvt_pk_bf16_f32 v33, v41, v42
	v_cvt_pk_bf16_f32 v34, v43, v44
	v_cvt_pk_bf16_f32 v35, v36, v35
	global_store_dwordx4 v[38:39], v[32:35], off
	s_nop 1
	v_mov_b32_e32 v34, v235
	s_nop 0
	v_mov_b32_e32 v33, v24
	v_mov_b32_e32 v24, v29
	v_mov_b32_e32 v29, v26
	v_mov_b32_e32 v26, v31
	v_mov_b32_e32 v31, v16
	v_mov_b32_e32 v16, v21
	v_mov_b32_e32 v21, v18
	v_mov_b32_e32 v18, v23
	v_mov_b32_e32 v32, v28
	v_mov_b32_e32 v28, v30
	v_mov_b32_e32 v30, v20
	v_mov_b32_e32 v20, v22
	v_add_u32_e32 v22, 0xa0, v142
	s_nop 0
	v_fmamk_f32 v23, v34, 0x3a800000, v156
	v_mul_f32_e32 v34, 0x4b800000, v23
	v_cmp_gt_f32_e32 vcc, s68, v23
	s_nop 1
	v_cndmask_b32_e32 v23, v23, v34, vcc
	v_rsq_f32_e32 v34, v23
	v_mad_i64_i32 v[22:23], s[56:57], v22, s69, v[116:117]
	v_lshl_add_u64 v[22:23], v[22:23], 0, v[118:119]
	v_mul_f32_e32 v35, 0x45800000, v34
	v_cndmask_b32_e32 v34, v34, v35, vcc
	v_pk_mul_f32 v[18:19], v[18:19], v[34:35] op_sel_hi:[1,0]
	v_pk_mul_f32 v[32:33], v[32:33], v[34:35] op_sel_hi:[1,0]
	v_pk_mul_f32 v[24:25], v[24:25], v[34:35] op_sel_hi:[1,0]
	v_pk_mul_f32 v[28:29], v[28:29], v[34:35] op_sel_hi:[1,0]
	v_pk_mul_f32 v[26:27], v[26:27], v[34:35] op_sel_hi:[1,0]
	v_pk_mul_f32 v[30:31], v[30:31], v[34:35] op_sel_hi:[1,0]
	v_pk_mul_f32 v[16:17], v[16:17], v[34:35] op_sel_hi:[1,0]
	v_pk_mul_f32 v[20:21], v[20:21], v[34:35] op_sel_hi:[1,0]
	v_mul_f32_e32 v41, 0xbfb8aa3b, v19
	v_mul_f32_e32 v34, 0xbfb8aa3b, v33
	v_mul_f32_e32 v35, 0xbfb8aa3b, v25
	v_mul_f32_e32 v36, 0xbfb8aa3b, v29
	v_mul_f32_e32 v37, 0xbfb8aa3b, v27
	v_mul_f32_e32 v38, 0xbfb8aa3b, v31
	v_mul_f32_e32 v39, 0xbfb8aa3b, v17
	v_mul_f32_e32 v40, 0xbfb8aa3b, v21
	v_exp_f32_e32 v41, v41
	v_exp_f32_e32 v34, v34
	v_exp_f32_e32 v35, v35
	v_exp_f32_e32 v36, v36
	v_exp_f32_e32 v37, v37
	v_exp_f32_e32 v38, v38
	v_exp_f32_e32 v39, v39
	v_exp_f32_e32 v40, v40
	v_add_f32_e32 v41, 1.0, v41
	v_add_f32_e32 v34, 1.0, v34
	v_add_f32_e32 v35, 1.0, v35
	v_add_f32_e32 v36, 1.0, v36
	v_add_f32_e32 v37, 1.0, v37
	v_add_f32_e32 v38, 1.0, v38
	v_add_f32_e32 v39, 1.0, v39
	v_add_f32_e32 v40, 1.0, v40
	v_rcp_f32_e32 v41, v41
	v_rcp_f32_e32 v34, v34
	v_rcp_f32_e32 v35, v35
	v_rcp_f32_e32 v36, v36
	v_rcp_f32_e32 v37, v37
	v_rcp_f32_e32 v38, v38
	v_rcp_f32_e32 v39, v39
	v_rcp_f32_e32 v40, v40
	v_mul_f32_e32 v19, v19, v41
	v_mul_f32_e32 v33, v33, v34
	v_mul_f32_e32 v25, v25, v35
	v_mul_f32_e32 v29, v29, v36
	v_mul_f32_e32 v27, v27, v37
	v_mul_f32_e32 v31, v31, v38
	v_mul_f32_e32 v17, v17, v39
	v_mul_f32_e32 v21, v21, v40
	v_mul_f32_e32 v19, v18, v19
	v_mul_f32_e32 v32, v32, v33
	v_mul_f32_e32 v24, v24, v25
	v_mul_f32_e32 v25, v28, v29
	v_mul_f32_e32 v26, v26, v27
	v_mul_f32_e32 v27, v30, v31
	v_mul_f32_e32 v28, v16, v17
	v_mul_f32_e32 v20, v20, v21
	v_cvt_pk_bf16_f32 v16, v32, v24
	v_cvt_pk_bf16_f32 v17, v25, v26
	v_cvt_pk_bf16_f32 v18, v27, v28
	v_cvt_pk_bf16_f32 v19, v20, v19
	global_store_dwordx4 v[22:23], v[16:19], off
	s_nop 1
	v_mov_b32_e32 v18, v236
	s_nop 0
	v_mov_b32_e32 v17, v8
	v_mov_b32_e32 v8, v13
	v_mov_b32_e32 v13, v10
	v_mov_b32_e32 v10, v15
	v_mov_b32_e32 v15, v4
	v_mov_b32_e32 v4, v1
	v_mov_b32_e32 v1, v6
	v_mov_b32_e32 v6, v3
	v_mov_b32_e32 v16, v12
	v_mov_b32_e32 v12, v14
	v_mov_b32_e32 v14, v0
	v_mov_b32_e32 v0, v2
	v_add_u32_e32 v2, 0xb0, v142
	s_nop 0
	v_fmamk_f32 v3, v18, 0x3a800000, v156
	v_mul_f32_e32 v18, 0x4b800000, v3
	v_cmp_gt_f32_e32 vcc, s68, v3
	s_nop 1
	v_cndmask_b32_e32 v3, v3, v18, vcc
	v_rsq_f32_e32 v20, v3
	v_mad_i64_i32 v[2:3], s[56:57], v2, s69, v[116:117]
	v_lshl_add_u64 v[18:19], v[2:3], 0, v[118:119]
	v_mul_f32_e32 v2, 0x45800000, v20
	v_cndmask_b32_e32 v2, v20, v2, vcc
	v_pk_mul_f32 v[16:17], v[16:17], v[2:3] op_sel_hi:[1,0]
	v_pk_mul_f32 v[8:9], v[8:9], v[2:3] op_sel_hi:[1,0]
	v_pk_mul_f32 v[12:13], v[12:13], v[2:3] op_sel_hi:[1,0]
	v_pk_mul_f32 v[10:11], v[10:11], v[2:3] op_sel_hi:[1,0]
	v_pk_mul_f32 v[14:15], v[14:15], v[2:3] op_sel_hi:[1,0]
	v_pk_mul_f32 v[4:5], v[4:5], v[2:3] op_sel_hi:[1,0]
	v_pk_mul_f32 v[0:1], v[0:1], v[2:3] op_sel_hi:[1,0]
	v_pk_mul_f32 v[2:3], v[6:7], v[2:3] op_sel_hi:[1,0]
	v_mul_f32_e32 v6, 0xbfb8aa3b, v17
	v_mul_f32_e32 v25, 0xbfb8aa3b, v3
	v_mul_f32_e32 v7, 0xbfb8aa3b, v9
	v_mul_f32_e32 v20, 0xbfb8aa3b, v13
	v_mul_f32_e32 v21, 0xbfb8aa3b, v11
	v_mul_f32_e32 v22, 0xbfb8aa3b, v15
	v_mul_f32_e32 v23, 0xbfb8aa3b, v5
	v_mul_f32_e32 v24, 0xbfb8aa3b, v1
	v_exp_f32_e32 v25, v25
	v_exp_f32_e32 v6, v6
	v_exp_f32_e32 v7, v7
	v_exp_f32_e32 v20, v20
	v_exp_f32_e32 v21, v21
	v_exp_f32_e32 v22, v22
	v_exp_f32_e32 v23, v23
	v_exp_f32_e32 v24, v24
	v_add_f32_e32 v25, 1.0, v25
	v_add_f32_e32 v6, 1.0, v6
	v_add_f32_e32 v7, 1.0, v7
	v_add_f32_e32 v20, 1.0, v20
	v_add_f32_e32 v21, 1.0, v21
	v_add_f32_e32 v22, 1.0, v22
	v_add_f32_e32 v23, 1.0, v23
	v_add_f32_e32 v24, 1.0, v24
	v_rcp_f32_e32 v25, v25
	v_rcp_f32_e32 v6, v6
	v_rcp_f32_e32 v7, v7
	v_rcp_f32_e32 v20, v20
	v_rcp_f32_e32 v21, v21
	v_rcp_f32_e32 v22, v22
	v_rcp_f32_e32 v23, v23
	v_rcp_f32_e32 v24, v24
	v_mul_f32_e32 v3, v3, v25
	v_mul_f32_e32 v6, v17, v6
	v_mul_f32_e32 v7, v9, v7
	v_mul_f32_e32 v9, v13, v20
	v_mul_f32_e32 v11, v11, v21
	v_mul_f32_e32 v13, v15, v22
	v_mul_f32_e32 v5, v5, v23
	v_mul_f32_e32 v1, v1, v24
	v_mul_f32_e32 v3, v2, v3
	v_mul_f32_e32 v6, v16, v6
	v_mul_f32_e32 v7, v8, v7
	v_mul_f32_e32 v8, v12, v9
	v_mul_f32_e32 v9, v10, v11
	v_mul_f32_e32 v10, v14, v13
	v_mul_f32_e32 v4, v4, v5
	v_mul_f32_e32 v5, v0, v1
	v_cvt_pk_bf16_f32 v0, v6, v7
	v_cvt_pk_bf16_f32 v1, v8, v9
	v_cvt_pk_bf16_f32 v2, v10, v4
	v_cvt_pk_bf16_f32 v3, v5, v3
	global_store_dwordx4 v[18:19], v[0:3], off
	s_cbranch_scc1 .LBB0_120
	buffer_wbl2 sc1
	s_waitcnt vmcnt(0)
	s_and_saveexec_b64 s[56:57], s[4:5]
	s_cbranch_execz .LBB0_119
	s_mov_b64 s[58:59], exec
	v_mbcnt_lo_u32_b32 v0, s58, 0
	v_mbcnt_hi_u32_b32 v0, s59, v0
	v_cmp_eq_u32_e32 vcc, 0, v0
	s_and_b64 s[62:63], exec, vcc
	s_mov_b64 exec, s[62:63]
	s_cbranch_execz .LBB0_119
	s_bcnt1_i32_b64 s3, s[58:59]
	v_mov_b32_e32 v0, s3
	global_atomic_add v131, v0, s[12:13]

; __device__ __forceinline__ unsigned cvt_pk_bf16(float lo, float hi) { unsigned r; asm volatile("v_cvt_pk_bf16_f32 %0, %1, %2" : "=v"(r) : "v"(lo), "v"(hi)); return r; }
;     __device__ __forceinline__ void operator()(const pg8::f32x4 (&acc)[2][2][4][2], const pg8::Unit& u, int wr, int wc, int fr, int fq) const {
;         const int row0 = u.pm * 256 + wr * 64 + fr, col0 = u.pn * 128 + wc * 32 + 8 * fq;
; #pragma unroll
;         for (int ai = 0; ai < 2; ++ai)
; #pragma unroll
;             for (int m = 0; m < 4; ++m) {
;                 const int row = row0 + ai * 128 + m * 16;
;                 const float rs = rsqrtf(rowsq[row] * (1.f / 1024.f) + 1e-6f);
;                 float h[8];
; #pragma unroll
;                 for (int n = 0; n < 2; ++n)
; #pragma unroll
;                     for (int j = 0; j < 4; ++j) { const float g = acc[ai][0][m][n][j] * rs, up = acc[ai][1][m][n][j] * rs; h[4 * n + j] = g * __builtin_amdgcn_rcpf(1.f + __expf(-g)) * up; }
;                 u32x4 w; w.x = cvt_pk_bf16(h[0], h[1]); w.y = cvt_pk_bf16(h[2], h[3]); w.z = cvt_pk_bf16(h[4], h[5]); w.w = cvt_pk_bf16(h[6], h[7]);
;                 *(u32x4*)(H + (size_t)row * DFF + col0) = w;
.LBB0_1756:
	v_lshl_add_u32 v142, s5, 8, v146
	v_ashrrev_i32_e32 v143, 31, v142
	v_lshl_add_u64 v[144:145], v[142:143], 2, s[20:21]
	global_load_dword v143, v[144:145], off
	global_load_dword v230, v[144:145], off offset:64
	global_load_dword v231, v[144:145], off offset:128
	global_load_dword v232, v[144:145], off offset:192
	global_load_dword v233, v[144:145], off offset:512
	global_load_dword v234, v[144:145], off offset:576
	global_load_dword v235, v[144:145], off offset:640
	global_load_dword v236, v[144:145], off offset:704
	v_lshl_or_b32 v154, s44, 7, v148
	v_mov_b32_e32 v159, v114
	v_mov_b32_e32 v114, v123
	v_mov_b32_e32 v156, v124
	v_mov_b32_e32 v157, v116
	v_mov_b32_e32 v116, v125
	v_mov_b32_e32 v124, v126
	v_mov_b32_e32 v125, v118
	v_mov_b32_e32 v118, v127
	v_mov_b32_e32 v126, v120
	v_mov_b32_e32 v127, v112
	v_mov_b32_e32 v112, v121
	v_mov_b32_e32 v158, v122
	v_mov_b64_e32 v[120:121], s[18:19]
	v_ashrrev_i32_e32 v155, 31, v154
	v_or_b32_e32 v162, 16, v142
	v_mad_i64_i32 v[160:161], s[44:45], v142, s68, v[120:121]
	v_lshlrev_b64 v[122:123], 1, v[154:155]
	v_ashrrev_i32_e32 v163, 31, v162
	v_lshl_add_u64 v[154:155], v[160:161], 0, v[122:123]
	v_lshl_add_u64 v[160:161], v[162:163], 2, s[20:21]
	s_cmp_lg_u32 s5, 64
	s_waitcnt vmcnt(0)
	v_fmamk_f32 v143, v143, 0x3a800000, v152
	v_mul_f32_e32 v153, 0x4b800000, v143
	v_cmp_gt_f32_e32 vcc, s67, v143
	s_nop 1
	v_cndmask_b32_e32 v143, v143, v153, vcc
	v_rsq_f32_e32 v143, v143
	s_nop 0
	v_mul_f32_e32 v153, 0x45800000, v143
	v_cndmask_b32_e32 v166, v143, v153, vcc
	v_pk_mul_f32 v[114:115], v[114:115], v[166:167] op_sel_hi:[1,0]
	v_pk_mul_f32 v[156:157], v[156:157], v[166:167] op_sel_hi:[1,0]
	v_pk_mul_f32 v[116:117], v[116:117], v[166:167] op_sel_hi:[1,0]
	v_pk_mul_f32 v[124:125], v[124:125], v[166:167] op_sel_hi:[1,0]
	v_pk_mul_f32 v[118:119], v[118:119], v[166:167] op_sel_hi:[1,0]
	v_pk_mul_f32 v[126:127], v[126:127], v[166:167] op_sel_hi:[1,0]
	v_pk_mul_f32 v[112:113], v[112:113], v[166:167] op_sel_hi:[1,0]
	v_pk_mul_f32 v[158:159], v[158:159], v[166:167] op_sel_hi:[1,0]
	v_mul_f32_e32 v169, 0xbfb8aa3b, v115
	v_mul_f32_e32 v143, 0xbfb8aa3b, v157
	v_mul_f32_e32 v153, 0xbfb8aa3b, v117
	v_mul_f32_e32 v163, 0xbfb8aa3b, v125
	v_mul_f32_e32 v165, 0xbfb8aa3b, v119
	v_mul_f32_e32 v166, 0xbfb8aa3b, v127
	v_mul_f32_e32 v167, 0xbfb8aa3b, v113
	v_mul_f32_e32 v168, 0xbfb8aa3b, v159
	v_exp_f32_e32 v169, v169
	v_exp_f32_e32 v143, v143
	v_exp_f32_e32 v153, v153
	v_exp_f32_e32 v163, v163
	v_exp_f32_e32 v165, v165
	v_exp_f32_e32 v166, v166
	v_exp_f32_e32 v167, v167
	v_exp_f32_e32 v168, v168
	v_add_f32_e32 v169, 1.0, v169
	v_add_f32_e32 v143, 1.0, v143
	v_add_f32_e32 v153, 1.0, v153
	v_add_f32_e32 v163, 1.0, v163
	v_add_f32_e32 v165, 1.0, v165
	v_add_f32_e32 v166, 1.0, v166
	v_add_f32_e32 v167, 1.0, v167
	v_add_f32_e32 v168, 1.0, v168
	v_rcp_f32_e32 v169, v169
	v_rcp_f32_e32 v143, v143
	v_rcp_f32_e32 v153, v153
	v_rcp_f32_e32 v163, v163
	v_rcp_f32_e32 v165, v165
	v_rcp_f32_e32 v166, v166
	v_rcp_f32_e32 v167, v167
	v_rcp_f32_e32 v168, v168
	v_mul_f32_e32 v115, v115, v169
	v_mul_f32_e32 v143, v157, v143
	v_mul_f32_e32 v117, v117, v153
	v_mul_f32_e32 v125, v125, v163
	v_mul_f32_e32 v119, v119, v165
	v_mul_f32_e32 v127, v127, v166
	v_mul_f32_e32 v113, v113, v167
	v_mul_f32_e32 v153, v159, v168
	v_mul_f32_e32 v115, v114, v115
	v_mul_f32_e32 v143, v156, v143
	v_mul_f32_e32 v116, v116, v117
	v_mul_f32_e32 v117, v124, v125
	v_mul_f32_e32 v118, v118, v119
	v_mul_f32_e32 v119, v126, v127
	v_mul_f32_e32 v124, v112, v113
	v_mul_f32_e32 v125, v158, v153
	v_cvt_pk_bf16_f32 v112, v143, v116
	v_cvt_pk_bf16_f32 v113, v117, v118
	v_cvt_pk_bf16_f32 v114, v119, v124
	v_cvt_pk_bf16_f32 v115, v125, v115
	global_store_dwordx4 v[154:155], v[112:115], off
	s_nop 1
	v_mov_b32_e32 v116, v230
	s_nop 0
	v_mov_b32_e32 v113, v100
	v_mov_b32_e32 v100, v109
	v_mov_b32_e32 v109, v102
	v_mov_b32_e32 v102, v111
	v_mov_b32_e32 v111, v96
	v_mov_b32_e32 v96, v105
	v_mov_b32_e32 v105, v98
	v_mov_b32_e32 v98, v107
	v_mov_b32_e32 v112, v108
	v_mov_b32_e32 v108, v110
	v_mov_b32_e32 v110, v104
	v_mov_b32_e32 v104, v106
	v_or_b32_e32 v106, 32, v142
	v_mad_i64_i32 v[114:115], s[44:45], v162, s68, v[120:121]
	v_lshl_add_u64 v[114:115], v[114:115], 0, v[122:123]
	s_nop 0
	v_fmamk_f32 v107, v116, 0x3a800000, v152
	v_mul_f32_e32 v116, 0x4b800000, v107
	v_cmp_gt_f32_e32 vcc, s67, v107
	s_nop 1
	v_cndmask_b32_e32 v107, v107, v116, vcc
	v_rsq_f32_e32 v118, v107
	v_ashrrev_i32_e32 v107, 31, v106
	v_lshl_add_u64 v[116:117], v[106:107], 2, s[20:21]
	v_mul_f32_e32 v107, 0x45800000, v118
	v_cndmask_b32_e32 v118, v118, v107, vcc
	v_pk_mul_f32 v[98:99], v[98:99], v[118:119] op_sel_hi:[1,0]
	v_pk_mul_f32 v[112:113], v[112:113], v[118:119] op_sel_hi:[1,0]
	v_pk_mul_f32 v[100:101], v[100:101], v[118:119] op_sel_hi:[1,0]
	v_pk_mul_f32 v[108:109], v[108:109], v[118:119] op_sel_hi:[1,0]
	v_pk_mul_f32 v[102:103], v[102:103], v[118:119] op_sel_hi:[1,0]
	v_pk_mul_f32 v[110:111], v[110:111], v[118:119] op_sel_hi:[1,0]
	v_pk_mul_f32 v[96:97], v[96:97], v[118:119] op_sel_hi:[1,0]
	v_pk_mul_f32 v[104:105], v[104:105], v[118:119] op_sel_hi:[1,0]
	v_mul_f32_e32 v143, 0xbfb8aa3b, v99
	v_mul_f32_e32 v107, 0xbfb8aa3b, v113
	v_mul_f32_e32 v118, 0xbfb8aa3b, v101
	v_mul_f32_e32 v119, 0xbfb8aa3b, v109
	v_mul_f32_e32 v124, 0xbfb8aa3b, v103
	v_mul_f32_e32 v125, 0xbfb8aa3b, v111
	v_mul_f32_e32 v126, 0xbfb8aa3b, v97
	v_mul_f32_e32 v127, 0xbfb8aa3b, v105
	v_exp_f32_e32 v143, v143
	v_exp_f32_e32 v107, v107
	v_exp_f32_e32 v118, v118
	v_exp_f32_e32 v119, v119
	v_exp_f32_e32 v124, v124
	v_exp_f32_e32 v125, v125
	v_exp_f32_e32 v126, v126
	v_exp_f32_e32 v127, v127
	v_add_f32_e32 v143, 1.0, v143
; __device__ __forceinline__ unsigned cvt_pk_bf16(float lo, float hi) { unsigned r; asm volatile("v_cvt_pk_bf16_f32 %0, %1, %2" : "=v"(r) : "v"(lo), "v"(hi)); return r; }
;     __device__ __forceinline__ void operator()(const pg8::f32x4 (&acc)[2][2][4][2], const pg8::Unit& u, int wr, int wc, int fr, int fq) const {
;         const int row0 = u.pm * 256 + wr * 64 + fr, col0 = u.pn * 128 + wc * 32 + 8 * fq;
; #pragma unroll
;         for (int ai = 0; ai < 2; ++ai)
; #pragma unroll
;             for (int m = 0; m < 4; ++m) {
;                 const int row = row0 + ai * 128 + m * 16;
;                 const float rs = rsqrtf(rowsq[row] * (1.f / 1024.f) + 1e-6f);
;                 float h[8];
; #pragma unroll
;                 for (int n = 0; n < 2; ++n)
; #pragma unroll
;                     for (int j = 0; j < 4; ++j) { const float g = acc[ai][0][m][n][j] * rs, up = acc[ai][1][m][n][j] * rs; h[4 * n + j] = g * __builtin_amdgcn_rcpf(1.f + __expf(-g)) * up; }
;                 u32x4 w; w.x = cvt_pk_bf16(h[0], h[1]); w.y = cvt_pk_bf16(h[2], h[3]); w.z = cvt_pk_bf16(h[4], h[5]); w.w = cvt_pk_bf16(h[6], h[7]);
;                 *(u32x4*)(H + (size_t)row * DFF + col0) = w;
	v_add_f32_e32 v107, 1.0, v107
	v_add_f32_e32 v118, 1.0, v118
	v_add_f32_e32 v119, 1.0, v119
	v_add_f32_e32 v124, 1.0, v124
	v_add_f32_e32 v125, 1.0, v125
	v_add_f32_e32 v126, 1.0, v126
	v_add_f32_e32 v127, 1.0, v127
	v_rcp_f32_e32 v143, v143
	v_rcp_f32_e32 v107, v107
	v_rcp_f32_e32 v118, v118
	v_rcp_f32_e32 v119, v119
	v_rcp_f32_e32 v124, v124
	v_rcp_f32_e32 v125, v125
	v_rcp_f32_e32 v126, v126
	v_rcp_f32_e32 v127, v127
	v_mul_f32_e32 v99, v99, v143
	v_mul_f32_e32 v107, v113, v107
	v_mul_f32_e32 v101, v101, v118
	v_mul_f32_e32 v109, v109, v119
	v_mul_f32_e32 v103, v103, v124
	v_mul_f32_e32 v111, v111, v125
	v_mul_f32_e32 v97, v97, v126
	v_mul_f32_e32 v105, v105, v127
	v_mul_f32_e32 v99, v98, v99
	v_mul_f32_e32 v107, v112, v107
	v_mul_f32_e32 v100, v100, v101
	v_mul_f32_e32 v101, v108, v109
	v_mul_f32_e32 v102, v102, v103
	v_mul_f32_e32 v103, v110, v111
	v_mul_f32_e32 v108, v96, v97
	v_mul_f32_e32 v104, v104, v105
	v_cvt_pk_bf16_f32 v96, v107, v100
	v_cvt_pk_bf16_f32 v97, v101, v102
	v_cvt_pk_bf16_f32 v98, v103, v108
	v_cvt_pk_bf16_f32 v99, v104, v99
	global_store_dwordx4 v[114:115], v[96:99], off
	s_nop 1
	v_mov_b32_e32 v100, v231
	s_nop 0
	v_mov_b32_e32 v97, v84
	v_mov_b32_e32 v84, v93
	v_mov_b32_e32 v93, v86
	v_mov_b32_e32 v86, v95
	v_mov_b32_e32 v95, v80
	v_mov_b32_e32 v80, v89
	v_mov_b32_e32 v89, v82
	v_mov_b32_e32 v82, v91
	v_mov_b32_e32 v96, v92
	v_mov_b32_e32 v92, v94
	v_mov_b32_e32 v94, v88
	v_mov_b32_e32 v88, v90
	v_or_b32_e32 v90, 48, v142
	v_mad_i64_i32 v[98:99], s[44:45], v106, s68, v[120:121]
	v_lshl_add_u64 v[98:99], v[98:99], 0, v[122:123]
	s_nop 0
	v_fmamk_f32 v91, v100, 0x3a800000, v152
	v_mul_f32_e32 v100, 0x4b800000, v91
	v_cmp_gt_f32_e32 vcc, s67, v91
	s_nop 1
	v_cndmask_b32_e32 v91, v91, v100, vcc
	v_rsq_f32_e32 v102, v91
	v_ashrrev_i32_e32 v91, 31, v90
	v_lshl_add_u64 v[100:101], v[90:91], 2, s[20:21]
	v_mul_f32_e32 v91, 0x45800000, v102
	v_cndmask_b32_e32 v102, v102, v91, vcc
	v_pk_mul_f32 v[82:83], v[82:83], v[102:103] op_sel_hi:[1,0]
	v_pk_mul_f32 v[96:97], v[96:97], v[102:103] op_sel_hi:[1,0]
	v_pk_mul_f32 v[84:85], v[84:85], v[102:103] op_sel_hi:[1,0]
	v_pk_mul_f32 v[92:93], v[92:93], v[102:103] op_sel_hi:[1,0]
	v_pk_mul_f32 v[86:87], v[86:87], v[102:103] op_sel_hi:[1,0]
	v_pk_mul_f32 v[94:95], v[94:95], v[102:103] op_sel_hi:[1,0]
	v_pk_mul_f32 v[80:81], v[80:81], v[102:103] op_sel_hi:[1,0]
	v_pk_mul_f32 v[88:89], v[88:89], v[102:103] op_sel_hi:[1,0]
	v_mul_f32_e32 v108, 0xbfb8aa3b, v83
	v_mul_f32_e32 v91, 0xbfb8aa3b, v97
	v_mul_f32_e32 v102, 0xbfb8aa3b, v85
	v_mul_f32_e32 v103, 0xbfb8aa3b, v93
	v_mul_f32_e32 v104, 0xbfb8aa3b, v87
	v_mul_f32_e32 v105, 0xbfb8aa3b, v95
	v_mul_f32_e32 v106, 0xbfb8aa3b, v81
	v_mul_f32_e32 v107, 0xbfb8aa3b, v89
	v_exp_f32_e32 v108, v108
	v_exp_f32_e32 v91, v91
	v_exp_f32_e32 v102, v102
	v_exp_f32_e32 v103, v103
	v_exp_f32_e32 v104, v104
	v_exp_f32_e32 v105, v105
	v_exp_f32_e32 v106, v106
	v_exp_f32_e32 v107, v107
	v_add_f32_e32 v108, 1.0, v108
	v_add_f32_e32 v91, 1.0, v91
	v_add_f32_e32 v102, 1.0, v102
	v_add_f32_e32 v103, 1.0, v103
	v_add_f32_e32 v104, 1.0, v104
	v_add_f32_e32 v105, 1.0, v105
	v_add_f32_e32 v106, 1.0, v106
	v_add_f32_e32 v107, 1.0, v107
	v_rcp_f32_e32 v108, v108
	v_rcp_f32_e32 v91, v91
	v_rcp_f32_e32 v102, v102
	v_rcp_f32_e32 v103, v103
	v_rcp_f32_e32 v104, v104
	v_rcp_f32_e32 v105, v105
	v_rcp_f32_e32 v106, v106
	v_rcp_f32_e32 v107, v107
	v_mul_f32_e32 v83, v83, v108
	v_mul_f32_e32 v91, v97, v91
	v_mul_f32_e32 v85, v85, v102
	v_mul_f32_e32 v93, v93, v103
	v_mul_f32_e32 v87, v87, v104
	v_mul_f32_e32 v95, v95, v105
	v_mul_f32_e32 v81, v81, v106
	v_mul_f32_e32 v89, v89, v107
	v_mul_f32_e32 v83, v82, v83
	v_mul_f32_e32 v91, v96, v91
	v_mul_f32_e32 v84, v84, v85
	v_mul_f32_e32 v85, v92, v93
	v_mul_f32_e32 v86, v86, v87
	v_mul_f32_e32 v87, v94, v95
	v_mul_f32_e32 v92, v80, v81
	v_mul_f32_e32 v88, v88, v89
	v_cvt_pk_bf16_f32 v80, v91, v84
	v_cvt_pk_bf16_f32 v81, v85, v86
	v_cvt_pk_bf16_f32 v82, v87, v92
	v_cvt_pk_bf16_f32 v83, v88, v83
	global_store_dwordx4 v[98:99], v[80:83], off
	s_nop 1
	v_mov_b32_e32 v82, v232
	s_nop 0
	v_mov_b32_e32 v80, v76
	v_mov_b32_e32 v76, v78
	v_mov_b32_e32 v78, v68
	v_mov_b32_e32 v68, v70
	v_mov_b32_e32 v81, v72
	v_mov_b32_e32 v72, v77
	v_mov_b32_e32 v77, v74
	v_mov_b32_e32 v74, v79
	v_mov_b32_e32 v79, v64
	v_mov_b32_e32 v64, v69
	v_mov_b32_e32 v69, v66
	v_mov_b32_e32 v66, v71
	s_nop 0
	v_fmamk_f32 v70, v82, 0x3a800000, v152
	v_mul_f32_e32 v71, 0x4b800000, v70
	v_cmp_gt_f32_e32 vcc, s67, v70
	s_nop 1
	v_cndmask_b32_e32 v70, v70, v71, vcc
	v_rsq_f32_e32 v82, v70
	v_mad_i64_i32 v[70:71], s[44:45], v90, s68, v[120:121]
	v_lshl_add_u64 v[70:71], v[70:71], 0, v[122:123]
	v_mul_f32_e32 v83, 0x45800000, v82
	v_cndmask_b32_e32 v82, v82, v83, vcc
	v_pk_mul_f32 v[66:67], v[66:67], v[82:83] op_sel_hi:[1,0]
	v_pk_mul_f32 v[80:81], v[80:81], v[82:83] op_sel_hi:[1,0]
	v_pk_mul_f32 v[72:73], v[72:73], v[82:83] op_sel_hi:[1,0]
	v_pk_mul_f32 v[76:77], v[76:77], v[82:83] op_sel_hi:[1,0]
	v_pk_mul_f32 v[74:75], v[74:75], v[82:83] op_sel_hi:[1,0]
	v_pk_mul_f32 v[78:79], v[78:79], v[82:83] op_sel_hi:[1,0]
	v_pk_mul_f32 v[64:65], v[64:65], v[82:83] op_sel_hi:[1,0]
	v_pk_mul_f32 v[68:69], v[68:69], v[82:83] op_sel_hi:[1,0]
	v_mul_f32_e32 v89, 0xbfb8aa3b, v67
	v_mul_f32_e32 v82, 0xbfb8aa3b, v81
	v_mul_f32_e32 v83, 0xbfb8aa3b, v73
	v_mul_f32_e32 v84, 0xbfb8aa3b, v77
	v_mul_f32_e32 v85, 0xbfb8aa3b, v75
	v_mul_f32_e32 v86, 0xbfb8aa3b, v79
	v_mul_f32_e32 v87, 0xbfb8aa3b, v65
	v_mul_f32_e32 v88, 0xbfb8aa3b, v69
	v_exp_f32_e32 v89, v89
	v_exp_f32_e32 v82, v82
	v_exp_f32_e32 v83, v83
	v_exp_f32_e32 v84, v84
	v_exp_f32_e32 v85, v85
	v_exp_f32_e32 v86, v86
	v_exp_f32_e32 v87, v87
; __device__ __forceinline__ unsigned cvt_pk_bf16(float lo, float hi) { unsigned r; asm volatile("v_cvt_pk_bf16_f32 %0, %1, %2" : "=v"(r) : "v"(lo), "v"(hi)); return r; }
;     __device__ __forceinline__ void operator()(const pg8::f32x4 (&acc)[2][2][4][2], const pg8::Unit& u, int wr, int wc, int fr, int fq) const {
;         const int row0 = u.pm * 256 + wr * 64 + fr, col0 = u.pn * 128 + wc * 32 + 8 * fq;
; #pragma unroll
;         for (int ai = 0; ai < 2; ++ai)
; #pragma unroll
;             for (int m = 0; m < 4; ++m) {
;                 const int row = row0 + ai * 128 + m * 16;
;                 const float rs = rsqrtf(rowsq[row] * (1.f / 1024.f) + 1e-6f);
;                 float h[8];
; #pragma unroll
;                 for (int n = 0; n < 2; ++n)
; #pragma unroll
;                     for (int j = 0; j < 4; ++j) { const float g = acc[ai][0][m][n][j] * rs, up = acc[ai][1][m][n][j] * rs; h[4 * n + j] = g * __builtin_amdgcn_rcpf(1.f + __expf(-g)) * up; }
;                 u32x4 w; w.x = cvt_pk_bf16(h[0], h[1]); w.y = cvt_pk_bf16(h[2], h[3]); w.z = cvt_pk_bf16(h[4], h[5]); w.w = cvt_pk_bf16(h[6], h[7]);
;                 *(u32x4*)(H + (size_t)row * DFF + col0) = w;
	v_exp_f32_e32 v88, v88
	v_add_f32_e32 v89, 1.0, v89
	v_add_f32_e32 v82, 1.0, v82
	v_add_f32_e32 v83, 1.0, v83
	v_add_f32_e32 v84, 1.0, v84
	v_add_f32_e32 v85, 1.0, v85
	v_add_f32_e32 v86, 1.0, v86
	v_add_f32_e32 v87, 1.0, v87
	v_add_f32_e32 v88, 1.0, v88
	v_rcp_f32_e32 v89, v89
	v_rcp_f32_e32 v82, v82
	v_rcp_f32_e32 v83, v83
	v_rcp_f32_e32 v84, v84
	v_rcp_f32_e32 v85, v85
	v_rcp_f32_e32 v86, v86
	v_rcp_f32_e32 v87, v87
	v_rcp_f32_e32 v88, v88
	v_mul_f32_e32 v67, v67, v89
	v_mul_f32_e32 v81, v81, v82
	v_mul_f32_e32 v73, v73, v83
	v_mul_f32_e32 v77, v77, v84
	v_mul_f32_e32 v75, v75, v85
	v_mul_f32_e32 v79, v79, v86
	v_mul_f32_e32 v65, v65, v87
	v_mul_f32_e32 v69, v69, v88
	v_mul_f32_e32 v67, v66, v67
	v_mul_f32_e32 v80, v80, v81
	v_mul_f32_e32 v72, v72, v73
	v_mul_f32_e32 v73, v76, v77
	v_mul_f32_e32 v74, v74, v75
	v_mul_f32_e32 v75, v78, v79
	v_mul_f32_e32 v76, v64, v65
	v_mul_f32_e32 v68, v68, v69
	v_cvt_pk_bf16_f32 v64, v80, v72
	v_cvt_pk_bf16_f32 v65, v73, v74
	v_cvt_pk_bf16_f32 v66, v75, v76
	v_cvt_pk_bf16_f32 v67, v68, v67
	global_store_dwordx4 v[70:71], v[64:67], off
	s_nop 1
	v_mov_b32_e32 v66, v233
	s_nop 0
	v_mov_b32_e32 v65, v56
	v_mov_b32_e32 v56, v61
	v_mov_b32_e32 v61, v58
	v_mov_b32_e32 v58, v63
	v_mov_b32_e32 v63, v48
	v_mov_b32_e32 v48, v53
	v_mov_b32_e32 v53, v50
	v_mov_b32_e32 v50, v55
	v_mov_b32_e32 v64, v60
	v_mov_b32_e32 v60, v62
	v_mov_b32_e32 v62, v52
	v_mov_b32_e32 v52, v54
	v_add_u32_e32 v54, 0x80, v142
	s_nop 0
	v_fmamk_f32 v55, v66, 0x3a800000, v152
	v_mul_f32_e32 v66, 0x4b800000, v55
	v_cmp_gt_f32_e32 vcc, s67, v55
	s_nop 1
	v_cndmask_b32_e32 v55, v55, v66, vcc
	v_rsq_f32_e32 v66, v55
	v_mad_i64_i32 v[54:55], s[44:45], v54, s68, v[120:121]
	v_lshl_add_u64 v[54:55], v[54:55], 0, v[122:123]
	v_mul_f32_e32 v67, 0x45800000, v66
	v_cndmask_b32_e32 v66, v66, v67, vcc
	v_pk_mul_f32 v[50:51], v[50:51], v[66:67] op_sel_hi:[1,0]
	v_pk_mul_f32 v[64:65], v[64:65], v[66:67] op_sel_hi:[1,0]
	v_pk_mul_f32 v[56:57], v[56:57], v[66:67] op_sel_hi:[1,0]
	v_pk_mul_f32 v[60:61], v[60:61], v[66:67] op_sel_hi:[1,0]
	v_pk_mul_f32 v[58:59], v[58:59], v[66:67] op_sel_hi:[1,0]
	v_pk_mul_f32 v[62:63], v[62:63], v[66:67] op_sel_hi:[1,0]
	v_pk_mul_f32 v[48:49], v[48:49], v[66:67] op_sel_hi:[1,0]
	v_pk_mul_f32 v[52:53], v[52:53], v[66:67] op_sel_hi:[1,0]
	v_mul_f32_e32 v73, 0xbfb8aa3b, v51
	v_mul_f32_e32 v66, 0xbfb8aa3b, v65
	v_mul_f32_e32 v67, 0xbfb8aa3b, v57
	v_mul_f32_e32 v68, 0xbfb8aa3b, v61
	v_mul_f32_e32 v69, 0xbfb8aa3b, v59
	v_mul_f32_e32 v70, 0xbfb8aa3b, v63
	v_mul_f32_e32 v71, 0xbfb8aa3b, v49
	v_mul_f32_e32 v72, 0xbfb8aa3b, v53
	v_exp_f32_e32 v73, v73
	v_exp_f32_e32 v66, v66
	v_exp_f32_e32 v67, v67
	v_exp_f32_e32 v68, v68
	v_exp_f32_e32 v69, v69
	v_exp_f32_e32 v70, v70
	v_exp_f32_e32 v71, v71
	v_exp_f32_e32 v72, v72
	v_add_f32_e32 v73, 1.0, v73
	v_add_f32_e32 v66, 1.0, v66
	v_add_f32_e32 v67, 1.0, v67
	v_add_f32_e32 v68, 1.0, v68
	v_add_f32_e32 v69, 1.0, v69
	v_add_f32_e32 v70, 1.0, v70
	v_add_f32_e32 v71, 1.0, v71
	v_add_f32_e32 v72, 1.0, v72
	v_rcp_f32_e32 v73, v73
	v_rcp_f32_e32 v66, v66
	v_rcp_f32_e32 v67, v67
	v_rcp_f32_e32 v68, v68
	v_rcp_f32_e32 v69, v69
	v_rcp_f32_e32 v70, v70
	v_rcp_f32_e32 v71, v71
	v_rcp_f32_e32 v72, v72
	v_mul_f32_e32 v51, v51, v73
	v_mul_f32_e32 v65, v65, v66
	v_mul_f32_e32 v57, v57, v67
	v_mul_f32_e32 v61, v61, v68
	v_mul_f32_e32 v59, v59, v69
	v_mul_f32_e32 v63, v63, v70
	v_mul_f32_e32 v49, v49, v71
	v_mul_f32_e32 v53, v53, v72
	v_mul_f32_e32 v51, v50, v51
	v_mul_f32_e32 v64, v64, v65
	v_mul_f32_e32 v56, v56, v57
	v_mul_f32_e32 v57, v60, v61
	v_mul_f32_e32 v58, v58, v59
	v_mul_f32_e32 v59, v62, v63
	v_mul_f32_e32 v60, v48, v49
	v_mul_f32_e32 v52, v52, v53
	v_cvt_pk_bf16_f32 v48, v64, v56
	v_cvt_pk_bf16_f32 v49, v57, v58
	v_cvt_pk_bf16_f32 v50, v59, v60
	v_cvt_pk_bf16_f32 v51, v52, v51
	global_store_dwordx4 v[54:55], v[48:51], off
	s_nop 1
	v_mov_b32_e32 v50, v234
	s_nop 0
	v_mov_b32_e32 v49, v40
	v_mov_b32_e32 v40, v45
	v_mov_b32_e32 v45, v42
	v_mov_b32_e32 v42, v47
	v_mov_b32_e32 v47, v32
	v_mov_b32_e32 v32, v37
	v_mov_b32_e32 v37, v34
	v_mov_b32_e32 v34, v39
	v_mov_b32_e32 v48, v44
	v_mov_b32_e32 v44, v46
	v_mov_b32_e32 v46, v36
	v_mov_b32_e32 v36, v38
	v_add_u32_e32 v38, 0x90, v142
	s_nop 0
	v_fmamk_f32 v39, v50, 0x3a800000, v152
	v_mul_f32_e32 v50, 0x4b800000, v39
	v_cmp_gt_f32_e32 vcc, s67, v39
	s_nop 1
	v_cndmask_b32_e32 v39, v39, v50, vcc
	v_rsq_f32_e32 v50, v39
	v_mad_i64_i32 v[38:39], s[44:45], v38, s68, v[120:121]
	v_lshl_add_u64 v[38:39], v[38:39], 0, v[122:123]
	v_mul_f32_e32 v51, 0x45800000, v50
	v_cndmask_b32_e32 v50, v50, v51, vcc
	v_pk_mul_f32 v[34:35], v[34:35], v[50:51] op_sel_hi:[1,0]
	v_pk_mul_f32 v[48:49], v[48:49], v[50:51] op_sel_hi:[1,0]
	v_pk_mul_f32 v[40:41], v[40:41], v[50:51] op_sel_hi:[1,0]
	v_pk_mul_f32 v[44:45], v[44:45], v[50:51] op_sel_hi:[1,0]
	v_pk_mul_f32 v[42:43], v[42:43], v[50:51] op_sel_hi:[1,0]
	v_pk_mul_f32 v[46:47], v[46:47], v[50:51] op_sel_hi:[1,0]
	v_pk_mul_f32 v[32:33], v[32:33], v[50:51] op_sel_hi:[1,0]
	v_pk_mul_f32 v[36:37], v[36:37], v[50:51] op_sel_hi:[1,0]
	v_mul_f32_e32 v57, 0xbfb8aa3b, v35
	v_mul_f32_e32 v50, 0xbfb8aa3b, v49
	v_mul_f32_e32 v51, 0xbfb8aa3b, v41
	v_mul_f32_e32 v52, 0xbfb8aa3b, v45
	v_mul_f32_e32 v53, 0xbfb8aa3b, v43
	v_mul_f32_e32 v54, 0xbfb8aa3b, v47
	v_mul_f32_e32 v55, 0xbfb8aa3b, v33
	v_mul_f32_e32 v56, 0xbfb8aa3b, v37
	v_exp_f32_e32 v57, v57
	v_exp_f32_e32 v50, v50
	v_exp_f32_e32 v51, v51
	v_exp_f32_e32 v52, v52
	v_exp_f32_e32 v53, v53
	v_exp_f32_e32 v54, v54
	v_exp_f32_e32 v55, v55
	v_exp_f32_e32 v56, v56
	v_add_f32_e32 v57, 1.0, v57
	v_add_f32_e32 v50, 1.0, v50
	v_add_f32_e32 v51, 1.0, v51
	v_add_f32_e32 v52, 1.0, v52
; __device__ __forceinline__ unsigned cvt_pk_bf16(float lo, float hi) { unsigned r; asm volatile("v_cvt_pk_bf16_f32 %0, %1, %2" : "=v"(r) : "v"(lo), "v"(hi)); return r; }
;     __device__ __forceinline__ void operator()(const pg8::f32x4 (&acc)[2][2][4][2], const pg8::Unit& u, int wr, int wc, int fr, int fq) const {
;         const int row0 = u.pm * 256 + wr * 64 + fr, col0 = u.pn * 128 + wc * 32 + 8 * fq;
; #pragma unroll
;         for (int ai = 0; ai < 2; ++ai)
; #pragma unroll
;             for (int m = 0; m < 4; ++m) {
;                 const int row = row0 + ai * 128 + m * 16;
;                 const float rs = rsqrtf(rowsq[row] * (1.f / 1024.f) + 1e-6f);
;                 float h[8];
; #pragma unroll
;                 for (int n = 0; n < 2; ++n)
; #pragma unroll
;                     for (int j = 0; j < 4; ++j) { const float g = acc[ai][0][m][n][j] * rs, up = acc[ai][1][m][n][j] * rs; h[4 * n + j] = g * __builtin_amdgcn_rcpf(1.f + __expf(-g)) * up; }
;                 u32x4 w; w.x = cvt_pk_bf16(h[0], h[1]); w.y = cvt_pk_bf16(h[2], h[3]); w.z = cvt_pk_bf16(h[4], h[5]); w.w = cvt_pk_bf16(h[6], h[7]);
;                 *(u32x4*)(H + (size_t)row * DFF + col0) = w;
;     __device__ __forceinline__ void done(const pg8::Unit& u) const {
;         if (u.pm == nM) { __builtin_amdgcn_fence(__ATOMIC_RELEASE, "agent"); if ((threadIdx.x & 63) == 0) __hip_atomic_fetch_add(cnt, 1u, __ATOMIC_RELAXED, __HIP_MEMORY_SCOPE_AGENT); }
;     }
	v_add_f32_e32 v53, 1.0, v53
	v_add_f32_e32 v54, 1.0, v54
	v_add_f32_e32 v55, 1.0, v55
	v_add_f32_e32 v56, 1.0, v56
	v_rcp_f32_e32 v57, v57
	v_rcp_f32_e32 v50, v50
	v_rcp_f32_e32 v51, v51
	v_rcp_f32_e32 v52, v52
	v_rcp_f32_e32 v53, v53
	v_rcp_f32_e32 v54, v54
	v_rcp_f32_e32 v55, v55
	v_rcp_f32_e32 v56, v56
	v_mul_f32_e32 v35, v35, v57
	v_mul_f32_e32 v49, v49, v50
	v_mul_f32_e32 v41, v41, v51
	v_mul_f32_e32 v45, v45, v52
	v_mul_f32_e32 v43, v43, v53
	v_mul_f32_e32 v47, v47, v54
	v_mul_f32_e32 v33, v33, v55
	v_mul_f32_e32 v37, v37, v56
	v_mul_f32_e32 v35, v34, v35
	v_mul_f32_e32 v48, v48, v49
	v_mul_f32_e32 v40, v40, v41
	v_mul_f32_e32 v41, v44, v45
	v_mul_f32_e32 v42, v42, v43
	v_mul_f32_e32 v43, v46, v47
	v_mul_f32_e32 v44, v32, v33
	v_mul_f32_e32 v36, v36, v37
	v_cvt_pk_bf16_f32 v32, v48, v40
	v_cvt_pk_bf16_f32 v33, v41, v42
	v_cvt_pk_bf16_f32 v34, v43, v44
	v_cvt_pk_bf16_f32 v35, v36, v35
	global_store_dwordx4 v[38:39], v[32:35], off
	s_nop 1
	v_mov_b32_e32 v34, v235
	s_nop 0
	v_mov_b32_e32 v33, v24
	v_mov_b32_e32 v24, v29
	v_mov_b32_e32 v29, v26
	v_mov_b32_e32 v26, v31
	v_mov_b32_e32 v31, v16
	v_mov_b32_e32 v16, v21
	v_mov_b32_e32 v21, v18
	v_mov_b32_e32 v18, v23
	v_mov_b32_e32 v32, v28
	v_mov_b32_e32 v28, v30
	v_mov_b32_e32 v30, v20
	v_mov_b32_e32 v20, v22
	v_add_u32_e32 v22, 0xa0, v142
	s_nop 0
	v_fmamk_f32 v23, v34, 0x3a800000, v152
	v_mul_f32_e32 v34, 0x4b800000, v23
	v_cmp_gt_f32_e32 vcc, s67, v23
	s_nop 1
	v_cndmask_b32_e32 v23, v23, v34, vcc
	v_rsq_f32_e32 v34, v23
	v_mad_i64_i32 v[22:23], s[44:45], v22, s68, v[120:121]
	v_lshl_add_u64 v[22:23], v[22:23], 0, v[122:123]
	v_mul_f32_e32 v35, 0x45800000, v34
	v_cndmask_b32_e32 v34, v34, v35, vcc
	v_pk_mul_f32 v[18:19], v[18:19], v[34:35] op_sel_hi:[1,0]
	v_pk_mul_f32 v[32:33], v[32:33], v[34:35] op_sel_hi:[1,0]
	v_pk_mul_f32 v[24:25], v[24:25], v[34:35] op_sel_hi:[1,0]
	v_pk_mul_f32 v[28:29], v[28:29], v[34:35] op_sel_hi:[1,0]
	v_pk_mul_f32 v[26:27], v[26:27], v[34:35] op_sel_hi:[1,0]
	v_pk_mul_f32 v[30:31], v[30:31], v[34:35] op_sel_hi:[1,0]
	v_pk_mul_f32 v[16:17], v[16:17], v[34:35] op_sel_hi:[1,0]
	v_pk_mul_f32 v[20:21], v[20:21], v[34:35] op_sel_hi:[1,0]
	v_mul_f32_e32 v41, 0xbfb8aa3b, v19
	v_mul_f32_e32 v34, 0xbfb8aa3b, v33
	v_mul_f32_e32 v35, 0xbfb8aa3b, v25
	v_mul_f32_e32 v36, 0xbfb8aa3b, v29
	v_mul_f32_e32 v37, 0xbfb8aa3b, v27
	v_mul_f32_e32 v38, 0xbfb8aa3b, v31
	v_mul_f32_e32 v39, 0xbfb8aa3b, v17
	v_mul_f32_e32 v40, 0xbfb8aa3b, v21
	v_exp_f32_e32 v41, v41
	v_exp_f32_e32 v34, v34
	v_exp_f32_e32 v35, v35
	v_exp_f32_e32 v36, v36
	v_exp_f32_e32 v37, v37
	v_exp_f32_e32 v38, v38
	v_exp_f32_e32 v39, v39
	v_exp_f32_e32 v40, v40
	v_add_f32_e32 v41, 1.0, v41
	v_add_f32_e32 v34, 1.0, v34
	v_add_f32_e32 v35, 1.0, v35
	v_add_f32_e32 v36, 1.0, v36
	v_add_f32_e32 v37, 1.0, v37
	v_add_f32_e32 v38, 1.0, v38
	v_add_f32_e32 v39, 1.0, v39
	v_add_f32_e32 v40, 1.0, v40
	v_rcp_f32_e32 v41, v41
	v_rcp_f32_e32 v34, v34
	v_rcp_f32_e32 v35, v35
	v_rcp_f32_e32 v36, v36
	v_rcp_f32_e32 v37, v37
	v_rcp_f32_e32 v38, v38
	v_rcp_f32_e32 v39, v39
	v_rcp_f32_e32 v40, v40
	v_mul_f32_e32 v19, v19, v41
	v_mul_f32_e32 v33, v33, v34
	v_mul_f32_e32 v25, v25, v35
	v_mul_f32_e32 v29, v29, v36
	v_mul_f32_e32 v27, v27, v37
	v_mul_f32_e32 v31, v31, v38
	v_mul_f32_e32 v17, v17, v39
	v_mul_f32_e32 v21, v21, v40
	v_mul_f32_e32 v19, v18, v19
	v_mul_f32_e32 v32, v32, v33
	v_mul_f32_e32 v24, v24, v25
	v_mul_f32_e32 v25, v28, v29
	v_mul_f32_e32 v26, v26, v27
	v_mul_f32_e32 v27, v30, v31
	v_mul_f32_e32 v28, v16, v17
	v_mul_f32_e32 v20, v20, v21
	v_cvt_pk_bf16_f32 v16, v32, v24
	v_cvt_pk_bf16_f32 v17, v25, v26
	v_cvt_pk_bf16_f32 v18, v27, v28
	v_cvt_pk_bf16_f32 v19, v20, v19
	global_store_dwordx4 v[22:23], v[16:19], off
	s_nop 1
	v_mov_b32_e32 v18, v236
	s_nop 0
	v_mov_b32_e32 v17, v8
	v_mov_b32_e32 v8, v13
	v_mov_b32_e32 v13, v10
	v_mov_b32_e32 v10, v15
	v_mov_b32_e32 v15, v4
	v_mov_b32_e32 v4, v1
	v_mov_b32_e32 v1, v6
	v_mov_b32_e32 v6, v3
	v_mov_b32_e32 v16, v12
	v_mov_b32_e32 v12, v14
	v_mov_b32_e32 v14, v0
	v_mov_b32_e32 v0, v2
	v_add_u32_e32 v2, 0xb0, v142
	s_nop 0
	v_fmamk_f32 v3, v18, 0x3a800000, v152
	v_mul_f32_e32 v18, 0x4b800000, v3
	v_cmp_gt_f32_e32 vcc, s67, v3
	s_nop 1
	v_cndmask_b32_e32 v3, v3, v18, vcc
	v_rsq_f32_e32 v20, v3
	v_mad_i64_i32 v[2:3], s[44:45], v2, s68, v[120:121]
	v_lshl_add_u64 v[18:19], v[2:3], 0, v[122:123]
	v_mul_f32_e32 v2, 0x45800000, v20
	v_cndmask_b32_e32 v2, v20, v2, vcc
	v_pk_mul_f32 v[16:17], v[16:17], v[2:3] op_sel_hi:[1,0]
	v_pk_mul_f32 v[8:9], v[8:9], v[2:3] op_sel_hi:[1,0]
	v_pk_mul_f32 v[12:13], v[12:13], v[2:3] op_sel_hi:[1,0]
	v_pk_mul_f32 v[10:11], v[10:11], v[2:3] op_sel_hi:[1,0]
	v_pk_mul_f32 v[14:15], v[14:15], v[2:3] op_sel_hi:[1,0]
	v_pk_mul_f32 v[4:5], v[4:5], v[2:3] op_sel_hi:[1,0]
	v_pk_mul_f32 v[0:1], v[0:1], v[2:3] op_sel_hi:[1,0]
	v_pk_mul_f32 v[2:3], v[6:7], v[2:3] op_sel_hi:[1,0]
	v_mul_f32_e32 v6, 0xbfb8aa3b, v17
	v_mul_f32_e32 v25, 0xbfb8aa3b, v3
	v_mul_f32_e32 v7, 0xbfb8aa3b, v9
	v_mul_f32_e32 v20, 0xbfb8aa3b, v13
	v_mul_f32_e32 v21, 0xbfb8aa3b, v11
	v_mul_f32_e32 v22, 0xbfb8aa3b, v15
	v_mul_f32_e32 v23, 0xbfb8aa3b, v5
	v_mul_f32_e32 v24, 0xbfb8aa3b, v1
	v_exp_f32_e32 v25, v25
	v_exp_f32_e32 v6, v6
	v_exp_f32_e32 v7, v7
	v_exp_f32_e32 v20, v20
	v_exp_f32_e32 v21, v21
	v_exp_f32_e32 v22, v22
	v_exp_f32_e32 v23, v23
	v_exp_f32_e32 v24, v24
	v_add_f32_e32 v25, 1.0, v25
	v_add_f32_e32 v6, 1.0, v6
	v_add_f32_e32 v7, 1.0, v7
	v_add_f32_e32 v20, 1.0, v20
	v_add_f32_e32 v21, 1.0, v21
	v_add_f32_e32 v22, 1.0, v22
	v_add_f32_e32 v23, 1.0, v23
	v_add_f32_e32 v24, 1.0, v24
	v_rcp_f32_e32 v25, v25
	v_rcp_f32_e32 v6, v6
	v_rcp_f32_e32 v7, v7
	v_rcp_f32_e32 v20, v20
	v_rcp_f32_e32 v21, v21
	v_rcp_f32_e32 v22, v22
	v_rcp_f32_e32 v23, v23
	v_rcp_f32_e32 v24, v24
	v_mul_f32_e32 v3, v3, v25
	v_mul_f32_e32 v6, v17, v6
	v_mul_f32_e32 v7, v9, v7
	v_mul_f32_e32 v9, v13, v20
	v_mul_f32_e32 v11, v11, v21
	v_mul_f32_e32 v13, v15, v22
	v_mul_f32_e32 v5, v5, v23
	v_mul_f32_e32 v1, v1, v24
	v_mul_f32_e32 v3, v2, v3
	v_mul_f32_e32 v6, v16, v6
	v_mul_f32_e32 v7, v8, v7
	v_mul_f32_e32 v8, v12, v9
	v_mul_f32_e32 v9, v10, v11
	v_mul_f32_e32 v10, v14, v13
	v_mul_f32_e32 v4, v4, v5
	v_mul_f32_e32 v5, v0, v1
	v_cvt_pk_bf16_f32 v0, v6, v7
	v_cvt_pk_bf16_f32 v1, v8, v9
	v_cvt_pk_bf16_f32 v2, v10, v4
	v_cvt_pk_bf16_f32 v3, v5, v3
	global_store_dwordx4 v[18:19], v[0:3], off
	s_cbranch_scc1 .LBB0_1761
	buffer_wbl2 sc1
	s_waitcnt vmcnt(0)
	s_and_saveexec_b64 s[44:45], s[6:7]
	s_cbranch_execz .LBB0_1760
	s_mov_b64 s[46:47], exec
	v_mbcnt_lo_u32_b32 v0, s46, 0
	v_mbcnt_hi_u32_b32 v0, s47, v0
	v_cmp_eq_u32_e32 vcc, 0, v0
	s_and_b64 s[48:49], exec, vcc
	s_mov_b64 exec, s[48:49]
	s_cbranch_execz .LBB0_1760
	s_bcnt1_i32_b64 s5, s[46:47]
	v_mov_b32_e32 v0, s5
	global_atomic_add v131, v0, s[14:15]
